# P4 (prompt out-projection) epilogue stores write-through (sc1) so the last grid barrier's L2 writeback finds the L2s clean
# baseline (speedup 1.0000x reference)
.LBB0_627:
	v_lshl_add_u32 v132, s16, 8, v142
	v_lshl_or_b32 v128, s44, 8, v143
	v_ashrrev_i32_e32 v133, 31, v132
	v_or_b32_e32 v128, s55, v128
	v_lshlrev_b64 v[130:131], 11, v[132:133]
	v_lshl_add_u64 v[130:131], s[2:3], 0, v[130:131]
	v_lshlrev_b32_e32 v128, 1, v128
	v_lshl_add_u64 v[130:131], v[130:131], 0, v[128:129]
	v_cvt_pk_bf16_f32 v124, v124, v125
	v_cvt_pk_bf16_f32 v125, v126, v127
	v_cvt_pk_bf16_f32 v126, v120, v121
	v_cvt_pk_bf16_f32 v127, v122, v123
	global_store_dwordx4 v[130:131], v[124:127], off sc1
	v_cvt_pk_bf16_f32 v112, v112, v113
	v_cvt_pk_bf16_f32 v113, v114, v115
	v_cvt_pk_bf16_f32 v114, v104, v105
	v_or_b32_e32 v104, 16, v132
	v_ashrrev_i32_e32 v105, 31, v104
	v_lshlrev_b64 v[104:105], 11, v[104:105]
	v_lshl_add_u64 v[104:105], s[2:3], 0, v[104:105]
	v_cvt_pk_bf16_f32 v115, v106, v107
	global_store_dwordx4 v[130:131], v[112:115], off offset:256 sc1
	s_nop 1
	v_lshl_add_u64 v[112:113], v[104:105], 0, v[128:129]
	v_cvt_pk_bf16_f32 v104, v116, v117
	v_cvt_pk_bf16_f32 v105, v118, v119
	v_cvt_pk_bf16_f32 v106, v108, v109
	v_cvt_pk_bf16_f32 v107, v110, v111
	global_store_dwordx4 v[112:113], v[104:107], off sc1
	v_cvt_pk_bf16_f32 v96, v96, v97
	v_cvt_pk_bf16_f32 v97, v98, v99
	v_cvt_pk_bf16_f32 v98, v88, v89
	v_or_b32_e32 v88, 32, v132
	v_ashrrev_i32_e32 v89, 31, v88
	v_lshlrev_b64 v[88:89], 11, v[88:89]
	v_lshl_add_u64 v[88:89], s[2:3], 0, v[88:89]
	v_cvt_pk_bf16_f32 v99, v90, v91
	global_store_dwordx4 v[112:113], v[96:99], off offset:256 sc1
	s_nop 1
	v_lshl_add_u64 v[96:97], v[88:89], 0, v[128:129]
	v_cvt_pk_bf16_f32 v88, v100, v101
	v_cvt_pk_bf16_f32 v89, v102, v103
	v_cvt_pk_bf16_f32 v90, v92, v93
	v_cvt_pk_bf16_f32 v91, v94, v95
	global_store_dwordx4 v[96:97], v[88:91], off sc1
	v_cvt_pk_bf16_f32 v80, v80, v81
	v_cvt_pk_bf16_f32 v81, v82, v83
	v_cvt_pk_bf16_f32 v82, v72, v73
	v_or_b32_e32 v72, 48, v132
	v_ashrrev_i32_e32 v73, 31, v72
	v_lshlrev_b64 v[72:73], 11, v[72:73]
	v_lshl_add_u64 v[72:73], s[2:3], 0, v[72:73]
	v_cvt_pk_bf16_f32 v83, v74, v75
	global_store_dwordx4 v[96:97], v[80:83], off offset:256 sc1
	s_nop 1
	v_lshl_add_u64 v[80:81], v[72:73], 0, v[128:129]
	v_cvt_pk_bf16_f32 v72, v84, v85
	v_cvt_pk_bf16_f32 v73, v86, v87
	v_cvt_pk_bf16_f32 v74, v76, v77
	v_cvt_pk_bf16_f32 v75, v78, v79
	global_store_dwordx4 v[80:81], v[72:75], off sc1
	v_cvt_pk_bf16_f32 v68, v68, v69
	v_cvt_pk_bf16_f32 v69, v70, v71
	v_cvt_pk_bf16_f32 v70, v64, v65
	v_cvt_pk_bf16_f32 v71, v66, v67
	global_store_dwordx4 v[80:81], v[68:71], off offset:256 sc1
	v_cvt_pk_bf16_f32 v60, v60, v61
	v_cvt_pk_bf16_f32 v61, v62, v63
	v_cvt_pk_bf16_f32 v62, v56, v57
	v_add_co_u32_e32 v56, vcc, s49, v130
	v_lshl_add_u64 v[64:65], v[130:131], 0, s[6:7]
	s_nop 0
	v_addc_co_u32_e32 v57, vcc, 0, v131, vcc
	v_cvt_pk_bf16_f32 v63, v58, v59
	global_store_dwordx4 v[56:57], v[60:63], off sc1
	v_cvt_pk_bf16_f32 v48, v48, v49
	v_cvt_pk_bf16_f32 v49, v50, v51
	v_cvt_pk_bf16_f32 v50, v40, v41
	v_cvt_pk_bf16_f32 v51, v42, v43
	global_store_dwordx4 v[64:65], v[48:51], off offset:256 sc1
	v_cvt_pk_bf16_f32 v40, v52, v53
	v_cvt_pk_bf16_f32 v41, v54, v55
	v_cvt_pk_bf16_f32 v42, v44, v45
	v_add_co_u32_e32 v44, vcc, s50, v130
	s_nop 0
	v_lshl_add_u64 v[48:49], v[130:131], 0, s[10:11]
	v_addc_co_u32_e32 v45, vcc, 0, v131, vcc
	v_cvt_pk_bf16_f32 v43, v46, v47
	global_store_dwordx4 v[44:45], v[40:43], off sc1
	v_cvt_pk_bf16_f32 v32, v32, v33
	v_cvt_pk_bf16_f32 v33, v34, v35
	v_cvt_pk_bf16_f32 v34, v24, v25
	v_cvt_pk_bf16_f32 v35, v26, v27
	global_store_dwordx4 v[48:49], v[32:35], off offset:256 sc1
	v_cvt_pk_bf16_f32 v24, v36, v37
	v_cvt_pk_bf16_f32 v25, v38, v39
	v_cvt_pk_bf16_f32 v26, v28, v29
	v_add_co_u32_e32 v28, vcc, s51, v130
	s_nop 0
	v_lshl_add_u64 v[32:33], v[130:131], 0, s[12:13]
	v_addc_co_u32_e32 v29, vcc, 0, v131, vcc
	v_cvt_pk_bf16_f32 v27, v30, v31
	global_store_dwordx4 v[28:29], v[24:27], off sc1
	v_cvt_pk_bf16_f32 v16, v16, v17
	v_cvt_pk_bf16_f32 v17, v18, v19
	v_cvt_pk_bf16_f32 v18, v8, v9
	v_cvt_pk_bf16_f32 v19, v10, v11
	global_store_dwordx4 v[32:33], v[16:19], off offset:256 sc1
	v_cvt_pk_bf16_f32 v8, v20, v21
	v_cvt_pk_bf16_f32 v9, v22, v23
	v_cvt_pk_bf16_f32 v10, v12, v13
	v_add_co_u32_e32 v12, vcc, s52, v130
	s_nop 0
	v_lshl_add_u64 v[16:17], v[130:131], 0, s[14:15]
	v_addc_co_u32_e32 v13, vcc, 0, v131, vcc
	v_cvt_pk_bf16_f32 v11, v14, v15
	global_store_dwordx4 v[12:13], v[8:11], off sc1
	v_cvt_pk_bf16_f32 v4, v4, v5
	v_cvt_pk_bf16_f32 v5, v6, v7
	v_cvt_pk_bf16_f32 v6, v0, v1
	v_cvt_pk_bf16_f32 v7, v2, v3
	global_store_dwordx4 v[16:17], v[4:7], off offset:256 sc1
	s_waitcnt vmcnt(0)
	s_barrier
